# MLA: O rescale and bf16 packs moved from the vector block to the start of the matrix block (rebalance)
# baseline (speedup 1.0000x reference)
; DI unsigned pk2(float lo, float hi) { const f32x2_t v = {lo, hi}; const bf16x2_t b = __builtin_convertvector(v, bf16x2_t); return __builtin_bit_cast(unsigned, b); }
; DI void mla_attn_phase(LAS unsigned char* lds, const bf16_t* Qg, const bf16_t* Kg, const bf16_t* Vtg, bf16_t* MIX) {
;     ...
;                     if (__any(alpha != 1.f)) {
; #pragma unroll
;                         for (int mt = 0; mt < 4; ++mt)
; #pragma unroll
;                             for (int i = 0; i < 16; ++i) o[mt][i] *= alpha; }
;                     bf16x8 pf[4];
; #pragma unroll
;                     for (int sp = 0; sp < 2; ++sp) { u32x4 p0, p1;
; #pragma unroll
;                         for (int j = 0; j < 4; ++j) { p0[j] = pk2(s0[8 * sp + 2 * j], s0[8 * sp + 2 * j + 1]); p1[j] = pk2(s1[8 * sp + 2 * j], s1[8 * sp + 2 * j + 1]); }
;                         pf[sp] = __builtin_bit_cast(bf16x8, p0); pf[2 + sp] = __builtin_bit_cast(bf16x8, p1); }
.Lmla_xb:
	s_barrier
	s_cmp_gt_i32 s40, s39
	s_cbranch_scc1 .LBB0_367
	v_cmp_neq_f32_e32 vcc, 1.0, v0
	s_cbranch_vccz .Lmla_noresc
	v_mul_f32_e32 v78, v0, v78
	v_mul_f32_e32 v79, v0, v79
	v_mul_f32_e32 v76, v0, v76
	v_mul_f32_e32 v77, v0, v77
	v_mul_f32_e32 v74, v0, v74
	v_mul_f32_e32 v75, v0, v75
	v_mul_f32_e32 v72, v0, v72
	v_mul_f32_e32 v73, v0, v73
	v_mul_f32_e32 v70, v0, v70
	v_mul_f32_e32 v71, v0, v71
	v_mul_f32_e32 v68, v0, v68
	v_mul_f32_e32 v69, v0, v69
	v_mul_f32_e32 v66, v0, v66
	v_mul_f32_e32 v67, v0, v67
	v_mul_f32_e32 v64, v0, v64
	v_mul_f32_e32 v65, v0, v65
	v_mul_f32_e32 v62, v0, v62
	v_mul_f32_e32 v63, v0, v63
	v_mul_f32_e32 v60, v0, v60
	v_mul_f32_e32 v61, v0, v61
	v_mul_f32_e32 v58, v0, v58
	v_mul_f32_e32 v59, v0, v59
	v_mul_f32_e32 v56, v0, v56
	v_mul_f32_e32 v57, v0, v57
	v_mul_f32_e32 v54, v0, v54
	v_mul_f32_e32 v55, v0, v55
	v_mul_f32_e32 v52, v0, v52
	v_mul_f32_e32 v53, v0, v53
	v_mul_f32_e32 v50, v0, v50
	v_mul_f32_e32 v51, v0, v51
	v_mul_f32_e32 v48, v0, v48
	v_mul_f32_e32 v49, v0, v49
	v_mul_f32_e32 v46, v0, v46
	v_mul_f32_e32 v47, v0, v47
	v_mul_f32_e32 v44, v0, v44
	v_mul_f32_e32 v45, v0, v45
	v_mul_f32_e32 v42, v0, v42
	v_mul_f32_e32 v43, v0, v43
	v_mul_f32_e32 v40, v0, v40
	v_mul_f32_e32 v41, v0, v41
	v_mul_f32_e32 v38, v0, v38
	v_mul_f32_e32 v39, v0, v39
	v_mul_f32_e32 v36, v0, v36
	v_mul_f32_e32 v37, v0, v37
	v_mul_f32_e32 v34, v0, v34
	v_mul_f32_e32 v35, v0, v35
	v_mul_f32_e32 v32, v0, v32
	v_mul_f32_e32 v33, v0, v33
	v_mul_f32_e32 v30, v0, v30
	v_mul_f32_e32 v31, v0, v31
	v_mul_f32_e32 v28, v0, v28
	v_mul_f32_e32 v29, v0, v29
	v_mul_f32_e32 v26, v0, v26
	v_mul_f32_e32 v27, v0, v27
	v_mul_f32_e32 v24, v0, v24
	v_mul_f32_e32 v25, v0, v25
	v_mul_f32_e32 v22, v0, v22
	v_mul_f32_e32 v23, v0, v23
	v_mul_f32_e32 v20, v0, v20
	v_mul_f32_e32 v21, v0, v21
	v_mul_f32_e32 v18, v0, v18
	v_mul_f32_e32 v19, v0, v19
	v_mul_f32_e32 v16, v0, v16
	v_mul_f32_e32 v17, v0, v17
.Lmla_noresc:
	v_cvt_pk_bf16_f32 v80, v80, v81
	v_cvt_pk_bf16_f32 v84, v96, v97
	v_cvt_pk_bf16_f32 v81, v82, v83
	v_cvt_pk_bf16_f32 v85, v98, v99
	v_cvt_pk_bf16_f32 v82, v226, v227
	v_cvt_pk_bf16_f32 v86, v100, v101
	v_cvt_pk_bf16_f32 v83, v218, v87
	v_cvt_pk_bf16_f32 v87, v102, v103
	v_cvt_pk_bf16_f32 v88, v88, v89
	v_cvt_pk_bf16_f32 v92, v104, v105
	v_cvt_pk_bf16_f32 v89, v90, v91
	v_cvt_pk_bf16_f32 v93, v106, v107
	v_cvt_pk_bf16_f32 v90, v219, v234
	v_cvt_pk_bf16_f32 v94, v108, v109
	v_cvt_pk_bf16_f32 v91, v235, v95
	v_cvt_pk_bf16_f32 v95, v110, v111
	s_waitcnt lgkmcnt(6)
	v_mfma_f32_32x32x16_bf16 v[64:79], v[144:147], v[80:83], v[64:79]
	v_mfma_f32_32x32x16_bf16 v[48:63], v[140:143], v[80:83], v[48:63]
	s_waitcnt lgkmcnt(0)
	v_mfma_f32_32x32x16_bf16 v[32:47], v[148:151], v[80:83], v[32:47]
	v_mfma_f32_32x32x16_bf16 v[16:31], v[152:155], v[80:83], v[16:31]
	ds_read_b128 v[80:83], v1 offset:13376
	ds_read_b128 v[96:99], v1 offset:17984
	ds_read_b128 v[100:103], v1 offset:22592
	ds_read_b128 v[104:107], v1 offset:27200
	v_mfma_f32_32x32x16_bf16 v[64:79], v[136:139], v[88:91], v[64:79]
	v_mfma_f32_32x32x16_bf16 v[48:63], v[12:15], v[88:91], v[48:63]
	v_mfma_f32_32x32x16_bf16 v[32:47], v[4:7], v[88:91], v[32:47]
	v_mfma_f32_32x32x16_bf16 v[16:31], v[8:11], v[88:91], v[16:31]
	ds_read_b128 v[4:7], v1 offset:13408
	ds_read_b128 v[8:11], v1 offset:18016
	ds_read_b128 v[12:15], v1 offset:22624
	ds_read_b128 v[88:91], v1 offset:27232
	s_waitcnt lgkmcnt(4)
	v_mfma_f32_32x32x16_bf16 v[64:79], v[80:83], v[84:87], v[64:79]
	v_mov_b32_e32 v233, v236
	v_mfma_f32_32x32x16_bf16 v[48:63], v[96:99], v[84:87], v[48:63]
	v_mfma_f32_32x32x16_bf16 v[32:47], v[100:103], v[84:87], v[32:47]
	v_mfma_f32_32x32x16_bf16 v[16:31], v[104:107], v[84:87], v[16:31]
	s_waitcnt lgkmcnt(0)
	v_mfma_f32_32x32x16_bf16 v[64:79], v[4:7], v[92:95], v[64:79]
	v_mfma_f32_32x32x16_bf16 v[48:63], v[8:11], v[92:95], v[48:63]
	v_mfma_f32_32x32x16_bf16 v[32:47], v[12:15], v[92:95], v[32:47]
	v_mfma_f32_32x32x16_bf16 v[16:31], v[88:91], v[92:95], v[16:31]
	s_branch .LBB0_371
